# ssd3 item start: LDS-reuse barrier moved down to the first LDS write (dt loads and scan chain overlap the barrier wait)
# baseline (speedup 1.0000x reference)
.LBB0_35:
	s_and_b32 s4, s29, 7
	v_lshl_or_b32 v162, s4, 2, v151
	v_or_b32_e32 v2, v162, v142
	v_readlane_b32 s8, v251, 2
	v_ashrrev_i32_e32 v3, 31, v2
	v_readlane_b32 s10, v251, 4
	v_readlane_b32 s11, v251, 5
	s_nop 0
	s_nop 0
	v_lshl_add_u64 v[2:3], v[2:3], 2, s[10:11]
	global_load_dword v3, v[2:3], off
	s_ashr_i32 s24, s29, 10
	s_bfe_u32 s2, s29, 0x60004
	s_ashr_i32 s25, s24, 31
	s_mul_i32 s1, s24, 0x4100
	s_lshl_b32 s50, s2, 8
	s_mul_hi_i32 s0, s24, 0x4100
	s_add_u32 s1, s1, s50
	s_addc_u32 s0, s0, 0
	s_add_u32 s6, s1, 0x100
	s_addc_u32 s67, s0, 0
	s_mov_b32 s0, 0x3fb8aa3b
	v_mov_b32_e32 v7, s67
	v_or_b32_e32 v6, s6, v152
	v_lshlrev_b64 v[6:7], 8, v[6:7]
	v_mov_b32_e32 v13, s67
	v_or_b32_e32 v12, s6, v156
	v_lshlrev_b64 v[12:13], 8, v[12:13]
	s_bfe_u32 s35, s29, 0x10003
	s_mov_b32 s7, s67
	s_lshl_b32 s8, s35, 7
	s_movk_i32 s3, 0x110
	v_lshl_add_u32 v189, s35, 9, v171
	s_mov_b32 s5, 0
	v_readlane_b32 s9, v251, 3
	v_readlane_b32 s12, v251, 6
	v_readlane_b32 s13, v251, 7
	v_readlane_b32 s14, v251, 8
	v_readlane_b32 s15, v251, 9
	v_readlane_b32 s16, v251, 10
	v_readlane_b32 s17, v251, 11
	v_readlane_b32 s18, v251, 12
	v_readlane_b32 s19, v251, 13
	v_readlane_b32 s20, v251, 14
	v_readlane_b32 s21, v251, 15
	v_readlane_b32 s22, v251, 16
	v_readlane_b32 s23, v251, 17
	s_waitcnt vmcnt(0)
	v_mul_f32_e32 v2, 0x3fb8aa3b, v3
	v_fma_f32 v4, v3, s0, -v2
	v_rndne_f32_e32 v5, v2
	v_fmac_f32_e32 v4, 0x32a5705f, v3
	v_sub_f32_e32 v2, v2, v5
	v_add_f32_e32 v2, v2, v4
	v_exp_f32_e32 v2, v2
	v_cvt_i32_f32_e32 v4, v5
	s_mov_b32 s0, 0xc2ce8ed0
	v_cmp_ngt_f32_e32 vcc, s0, v3
	s_mov_b32 s0, 0x42b17218
	v_ldexp_f32 v4, v2, v4
	v_cndmask_b32_e32 v4, 0, v4, vcc
	v_cmp_nlt_f32_e32 vcc, s0, v3
	v_mov_b32_e32 v5, v1
	v_readlane_b32 s0, v254, 9
	v_cndmask_b32_e32 v10, v219, v4, vcc
	v_lshlrev_b32_e32 v4, 2, v162
	v_lshl_add_u64 v[8:9], v[146:147], 0, v[4:5]
	v_mov_b32_e32 v5, s67
	v_or_b32_e32 v4, s6, v144
	v_lshlrev_b64 v[4:5], 8, v[4:5]
	v_lshl_add_u64 v[4:5], v[8:9], 0, v[4:5]
	v_lshl_add_u64 v[6:7], v[8:9], 0, v[6:7]
	global_load_dword v4, v[4:5], off
	v_readlane_b32 s1, v254, 10
	global_load_dword v5, v[6:7], off
	v_mov_b32_e32 v7, s67
	v_or_b32_e32 v6, s6, v154
	v_lshlrev_b64 v[6:7], 8, v[6:7]
	v_lshl_add_u64 v[6:7], v[8:9], 0, v[6:7]
	v_lshl_add_u64 v[8:9], v[8:9], 0, v[12:13]
	global_load_dword v6, v[6:7], off
	v_mov_b32_e32 v2, 0
	global_load_dword v7, v[8:9], off
	v_mov_b32_e32 v34, v2
	v_mov_b32_e32 v35, v2
	v_mov_b32_e32 v36, v2
	v_mov_b32_e32 v37, v2
	v_mov_b32_e32 v38, v2
	v_mov_b32_e32 v39, v2
	v_mov_b32_e32 v40, v2
	v_mov_b32_e32 v41, v2
	v_mov_b32_e32 v42, v2
	v_mov_b32_e32 v43, v2
	v_mov_b32_e32 v44, v2
	v_mov_b32_e32 v45, v2
	v_mov_b32_e32 v46, v2
	v_mov_b32_e32 v47, v2
	v_mov_b32_e32 v48, v2
	v_mov_b32_e32 v49, v2
	v_mov_b32_e32 v18, v2
	v_mov_b32_e32 v19, v2
	v_mov_b32_e32 v20, v2
	v_mov_b32_e32 v21, v2
	v_mov_b32_e32 v22, v2
	v_mov_b32_e32 v23, v2
	v_mov_b32_e32 v24, v2
	v_mov_b32_e32 v25, v2
	v_mov_b32_e32 v26, v2
	v_mov_b32_e32 v27, v2
	v_mov_b32_e32 v28, v2
	v_mov_b32_e32 v29, v2
	v_mov_b32_e32 v30, v2
	v_mov_b32_e32 v31, v2
	v_mov_b32_e32 v32, v2
	v_mov_b32_e32 v33, v2
	v_mov_b32_e32 v50, v2
	v_mov_b32_e32 v51, v2
	v_mov_b32_e32 v52, v2
	v_mov_b32_e32 v53, v2
	v_mov_b32_e32 v54, v2
	v_mov_b32_e32 v55, v2
	v_mov_b32_e32 v56, v2
	v_mov_b32_e32 v57, v2
	v_mov_b32_e32 v58, v2
	v_mov_b32_e32 v59, v2
	v_mov_b32_e32 v60, v2
	v_mov_b32_e32 v61, v2
	v_mov_b32_e32 v62, v2
	v_mov_b32_e32 v63, v2
	v_mov_b32_e32 v64, v2
	v_mov_b32_e32 v65, v2
	s_waitcnt vmcnt(2)
	v_pk_mul_f32 v[8:9], v[4:5], v[10:11] op_sel_hi:[1,0] neg_lo:[0,1] neg_hi:[0,1]
	s_nop 0
	v_pk_fma_f32 v[12:13], v[4:5], v[10:11], v[8:9] op_sel:[0,0,1] op_sel_hi:[1,0,0] neg_lo:[0,1,0] neg_hi:[0,1,0]
	s_waitcnt vmcnt(0)
	v_mul_f32_e64 v14, v7, -v10
	v_mov_b32_e32 v9, v12
	v_pk_fma_f32 v[12:13], v[6:7], v[10:11], v[12:13] op_sel_hi:[1,0,1] neg_lo:[0,1,0] neg_hi:[0,1,0]
	s_nop 0
	v_pk_add_f32 v[14:15], v[12:13], v[14:15] op_sel_hi:[1,0]
	ds_bpermute_b32 v3, v143, v14
	v_mov_b32_e32 v13, v14
	s_waitcnt lgkmcnt(0)
	v_add_f32_e32 v3, v14, v3
	v_cndmask_b32_e64 v3, v3, v14, s[0:1]
	ds_bpermute_b32 v11, v153, v3
	v_readlane_b32 s0, v254, 11
	v_readlane_b32 s1, v254, 12
	s_waitcnt lgkmcnt(0)
	v_add_f32_e32 v11, v3, v11
	v_cndmask_b32_e64 v3, v11, v3, s[0:1]
	ds_bpermute_b32 v11, v155, v3
	v_readlane_b32 s0, v254, 13
	v_readlane_b32 s1, v254, 14
	s_waitcnt lgkmcnt(0)
	v_add_f32_e32 v11, v3, v11
	v_cndmask_b32_e64 v3, v11, v3, s[0:1]
	ds_bpermute_b32 v11, v157, v3
	v_readlane_b32 s0, v254, 15
	v_readlane_b32 s1, v254, 16
	s_waitcnt lgkmcnt(0)
	v_add_f32_e32 v11, v3, v11
	v_cndmask_b32_e64 v3, v11, v3, s[0:1]
	ds_bpermute_b32 v11, v163, v3
	v_readlane_b32 s0, v254, 17
	v_readlane_b32 s1, v254, 18
	s_waitcnt lgkmcnt(0)
	v_add_f32_e32 v11, v3, v11
	v_cndmask_b32_e64 v3, v11, v3, s[0:1]
	ds_bpermute_b32 v11, v166, v3
	v_readlane_b32 s0, v254, 19
	v_readlane_b32 s1, v254, 20
	s_waitcnt lgkmcnt(0)
	v_add_f32_e32 v11, v3, v11
	v_cndmask_b32_e64 v3, v11, v3, s[0:1]
	v_sub_f32_e32 v16, v3, v14
	ds_bpermute_b32 v14, v167, v3
	v_pk_add_f32 v[8:9], v[8:9], v[16:17] op_sel_hi:[1,0]
	v_pk_add_f32 v[12:13], v[12:13], v[16:17] op_sel_hi:[1,0]
	v_readlane_b32 s0, v255, 10
	v_readlane_b32 s1, v255, 11
	s_waitcnt lgkmcnt(0)
	v_pk_add_f32 v[16:17], v[14:15], v[8:9] op_sel_hi:[0,1] neg_lo:[0,1] neg_hi:[0,1]
	v_pk_add_f32 v[14:15], v[14:15], v[12:13] op_sel_hi:[0,1] neg_lo:[0,1] neg_hi:[0,1]
	v_pk_fma_f32 v[16:17], v[4:5], v[10:11], v[16:17] op_sel_hi:[1,0,1] neg_lo:[0,1,0] neg_hi:[0,1,0]
	v_pk_fma_f32 v[10:11], v[6:7], v[10:11], v[14:15] op_sel_hi:[1,0,1] neg_lo:[0,1,0] neg_hi:[0,1,0]
	v_cndmask_b32_e64 v9, v17, v9, s[0:1]
	v_cndmask_b32_e64 v8, v16, v8, s[0:1]
	v_cndmask_b32_e64 v11, v11, v13, s[0:1]
	v_cndmask_b32_e64 v10, v10, v12, s[0:1]
	v_writelane_b32 v255, s6, 8
	s_or_b32 s66, s6, s8
	v_mov_b32_e32 v3, v179
	s_lshl_b32 s0, s4, 8
	s_barrier
	ds_write_b128 v176, v[8:11]
	ds_write_b128 v177, v[4:7]
	s_add_u32 s0, s38, s0
	v_lshlrev_b32_e32 v4, 4, v3
	v_ashrrev_i32_e32 v12, 4, v3
	s_addc_u32 s1, s39, 0
	v_and_b32_e32 v4, 0xf0, v4
	v_mov_b32_e32 v5, v1
	v_ashrrev_i32_e32 v13, 31, v12
	v_writelane_b32 v255, s7, 9
	v_lshl_add_u64 v[6:7], s[0:1], 0, v[4:5]
	s_mov_b64 s[6:7], 0x1800
	v_add_u32_e32 v10, 32, v4
	v_lshl_add_u64 v[4:5], s[66:67], 0, v[12:13]
	v_lshl_add_u64 v[8:9], v[6:7], 0, s[6:7]
	v_lshlrev_b64 v[4:5], 13, v[4:5]
	v_lshl_add_u64 v[4:5], v[8:9], 0, v[4:5]
	global_load_dwordx4 v[200:203], v[4:5], off
	v_mad_u64_u32 v[12:13], s[6:7], v12, s3, v[10:11]
	v_mov_b32_e32 v222, v12
	s_lshl_b32 s2, s2, 19
	v_mov_b32_e32 v14, v2
	v_mov_b32_e32 v15, v2
	v_mov_b32_e32 v16, v2
	v_mov_b32_e32 v17, v2
	v_add_u32_e32 v4, 0x200, v3
	v_ashrrev_i32_e32 v12, 4, v4
	v_ashrrev_i32_e32 v13, 31, v12
	v_lshl_add_u64 v[4:5], s[66:67], 0, v[12:13]
	v_lshlrev_b64 v[4:5], 13, v[4:5]
	v_lshl_add_u64 v[4:5], v[8:9], 0, v[4:5]
	global_load_dwordx4 v[204:207], v[4:5], off
	v_mad_u64_u32 v[12:13], s[6:7], v12, s3, v[10:11]
	v_mov_b32_e32 v223, v12
	v_add_u32_e32 v4, 0x400, v3
	v_ashrrev_i32_e32 v12, 4, v4
	v_ashrrev_i32_e32 v13, 31, v12
	v_lshl_add_u64 v[4:5], s[66:67], 0, v[12:13]
	v_lshlrev_b64 v[4:5], 13, v[4:5]
	v_lshl_add_u64 v[4:5], v[8:9], 0, v[4:5]
	global_load_dwordx4 v[208:211], v[4:5], off
	v_mad_u64_u32 v[12:13], s[6:7], v12, s3, v[10:11]
	v_mov_b32_e32 v224, v12
	v_add_u32_e32 v3, 0x600, v3
	v_ashrrev_i32_e32 v12, 4, v3
	v_ashrrev_i32_e32 v13, 31, v12
	v_lshl_add_u64 v[4:5], s[66:67], 0, v[12:13]
	v_lshlrev_b64 v[4:5], 13, v[4:5]
	v_lshl_add_u64 v[4:5], v[8:9], 0, v[4:5]
	global_load_dwordx4 v[212:215], v[4:5], off
	v_mad_u64_u32 v[8:9], s[6:7], v12, s3, v[10:11]
	s_mov_b32 s3, s51
	v_mov_b32_e32 v3, v2
	v_mov_b32_e32 v9, v2
	v_mov_b32_e32 v10, v2
	v_mov_b32_e32 v11, v2
	v_mov_b32_e32 v12, v2
	v_mov_b32_e32 v13, v2
	s_waitcnt vmcnt(3)
	ds_write_b128 v222, v[200:203]
	s_waitcnt vmcnt(2)
	ds_write_b128 v223, v[204:207]
	s_waitcnt vmcnt(1)
	ds_write_b128 v224, v[208:211]
	s_waitcnt vmcnt(0)
	ds_write_b128 v8, v[212:215]
	v_lshlrev_b32_e32 v4, 14, v162
	v_mov_b32_e32 v5, v1
	v_lshl_add_u64 v[6:7], v[148:149], 0, s[2:3]
	v_lshl_add_u64 v[164:165], v[6:7], 0, v[4:5]
	s_mov_b64 s[2:3], -1
	v_mov_b32_e32 v4, v2
	v_mov_b32_e32 v5, v2
	v_mov_b32_e32 v6, v2
	v_mov_b32_e32 v7, v2
	v_mov_b32_e32 v8, v2
	s_waitcnt lgkmcnt(0)
	s_barrier
